# NA tiles: next tile's Q and K rows 0-5 requested before the softmax/PV of the current tile (cross-tile prefetch)
# baseline (speedup 1.0000x reference)
.LBB0_1072:
	s_cmp_gt_i32 s66, 1
	s_mov_b64 s[0:1], -1
	s_cbranch_scc0 .LBB0_1115
	s_mov_b64 exec, -1
	v_writelane_b32 v245, s0, 0
	v_writelane_b32 v245, s1, 1
	v_writelane_b32 v245, s2, 2
	v_writelane_b32 v245, s3, 3
	v_writelane_b32 v245, s4, 4
	v_writelane_b32 v245, s5, 5
	v_writelane_b32 v245, s6, 6
	v_writelane_b32 v245, s7, 7
	v_writelane_b32 v245, s8, 8
	v_writelane_b32 v245, s9, 9
	v_writelane_b32 v245, s10, 10
	v_writelane_b32 v245, s11, 11
	v_writelane_b32 v245, s12, 12
	v_writelane_b32 v245, s13, 13
	v_writelane_b32 v245, s14, 14
	v_writelane_b32 v245, s15, 15
	v_writelane_b32 v245, s16, 16
	v_writelane_b32 v245, s17, 17
	v_writelane_b32 v245, s18, 18
	v_writelane_b32 v245, s19, 19
	v_writelane_b32 v245, s20, 20
	v_writelane_b32 v245, s21, 21
	v_writelane_b32 v245, s22, 22
	v_writelane_b32 v245, s23, 23
	v_writelane_b32 v245, s24, 24
	v_writelane_b32 v245, s25, 25
	v_writelane_b32 v245, s26, 26
	v_writelane_b32 v245, s27, 27
	v_writelane_b32 v245, s28, 28
	v_writelane_b32 v245, s29, 29
	v_writelane_b32 v245, s30, 30
	v_writelane_b32 v245, s31, 31
	v_writelane_b32 v245, s32, 32
	v_writelane_b32 v245, s33, 33
	v_writelane_b32 v245, s34, 34
	v_writelane_b32 v245, s35, 35
	v_writelane_b32 v245, s36, 36
	v_writelane_b32 v245, s37, 37
	v_writelane_b32 v245, s38, 38
	v_writelane_b32 v245, s39, 39
	v_writelane_b32 v245, s40, 40
	v_writelane_b32 v245, s41, 41
	v_writelane_b32 v245, s42, 42
	v_writelane_b32 v245, s43, 43
	v_writelane_b32 v245, s44, 44
	v_writelane_b32 v245, s45, 45
	v_writelane_b32 v245, s46, 46
	v_writelane_b32 v245, s47, 47
	v_writelane_b32 v245, s48, 48
	v_writelane_b32 v245, s49, 49
	v_writelane_b32 v245, s50, 50
	v_writelane_b32 v245, s51, 51
	v_writelane_b32 v245, s52, 52
	v_writelane_b32 v245, s53, 53
	v_writelane_b32 v245, s54, 54
	v_writelane_b32 v245, s55, 55
	v_writelane_b32 v245, s56, 56
	v_writelane_b32 v245, s57, 57
	v_writelane_b32 v245, s58, 58
	v_writelane_b32 v245, s59, 59
	v_writelane_b32 v245, s60, 60
	v_writelane_b32 v245, s61, 61
	v_writelane_b32 v245, s62, 62
	v_writelane_b32 v245, s63, 63
	v_writelane_b32 v244, s64, 0
	v_writelane_b32 v244, s65, 1
	v_writelane_b32 v244, s66, 2
	v_writelane_b32 v244, s67, 3
	v_writelane_b32 v244, s68, 4
	v_writelane_b32 v244, s69, 5
	v_writelane_b32 v244, s70, 6
	v_writelane_b32 v244, s71, 7
	v_writelane_b32 v244, s72, 8
	v_writelane_b32 v244, s73, 9
	v_writelane_b32 v244, s74, 10
	v_writelane_b32 v244, s75, 11
	v_writelane_b32 v244, s76, 12
	v_writelane_b32 v244, s77, 13
	v_writelane_b32 v244, s78, 14
	v_writelane_b32 v244, s79, 15
	v_lshrrev_b32_e32 v235, 6, v225
	v_and_b32_e32 v246, 63, v225
	s_load_dwordx2 s[10:11], s[100:101], 0xb0
	s_load_dwordx2 s[12:13], s[100:101], 0x28
	v_readfirstlane_b32 s4, v235
	v_and_b32_e32 v236, 15, v246
	v_lshrrev_b32_e32 v237, 4, v246
	s_nop 3
	s_and_b32 s5, s4, 3
	s_lshr_b32 s6, s4, 2
	s_lshl_b32 s7, s99, 1
	s_add_u32 s7, s7, s6
	s_lshl_b32 s8, s5, 4
	s_sub_i32 s8, s8, 8
	s_max_i32 s8, s8, 0
	s_min_i32 s8, s8, 32
	s_lshl_b32 s9, s5, 4
	v_lshrrev_b32_e32 v240, 2, v236
	v_and_b32_e32 v241, 3, v236
	v_lshl_add_u32 v240, v240, 3, v241
	v_lshlrev_b32_e32 v240, 10, v240
	v_lshl_add_u32 v218, v237, 4, v240
	v_add_u32_e32 v219, 0x1000, v218
	v_lshlrev_b32_e32 v240, 12, v236
	v_lshl_add_u32 v220, v237, 4, v240
	v_lshlrev_b32_e32 v240, 10, v236
	v_lshl_add_u32 v221, v237, 4, v240
	v_mul_u32_u24_e32 v240, 0xc00, v236
	v_lshl_add_u32 v222, v237, 3, v240
	v_xor_b32_e32 v223, 16, v246
	v_lshlrev_b32_e32 v223, 2, v223
	v_xor_b32_e32 v232, 32, v246
	v_lshlrev_b32_e32 v232, 2, v232
	s_lshr_b32 s36, s8, 3
	v_add_u32_e32 v136, s36, v237
	v_xor_b32_e32 v136, v136, v236
	v_lshlrev_b32_e32 v136, 4, v136
	v_lshl_or_b32 v136, v236, 10, v136
	s_lshl_b32 s36, s6, 16
	v_or_b32_e32 v136, s36, v136
	s_lshl_b32 s39, s5, 14
	s_add_u32 s39, s39, s36
	s_add_u32 s39, s39, 16
	v_add_u32_e32 v240, s9, v236
	v_lshl_add_u32 v241, v237, 3, s8
	v_sub_u32_e32 v235, v241, v240
	v_subrev_u32_e32 v240, 8, v240
	v_med3_i32 v240, v240, 0, 48
	v_sub_u32_e32 v241, v241, v240
	v_add_u32_e32 v240, 0, v235
	v_med3_i32 v240, v240, -15, 15
	v_add_u32_e32 v240, 15, v240
	v_lshlrev_b32_e32 v210, 2, v240
	v_add_u32_e32 v240, 0, v241
	v_cmp_gt_u32_e64 s[40:41], 16, v240
	v_add_u32_e32 v240, 1, v235
	v_med3_i32 v240, v240, -15, 15
	v_add_u32_e32 v240, 15, v240
	v_lshlrev_b32_e32 v211, 2, v240
	v_add_u32_e32 v240, 1, v241
	v_cmp_gt_u32_e64 s[42:43], 16, v240
	v_add_u32_e32 v240, 2, v235
	v_med3_i32 v240, v240, -15, 15
	v_add_u32_e32 v240, 15, v240
	v_lshlrev_b32_e32 v212, 2, v240
	v_add_u32_e32 v240, 2, v241
	v_cmp_gt_u32_e64 s[44:45], 16, v240
	v_add_u32_e32 v240, 3, v235
	v_med3_i32 v240, v240, -15, 15
	v_add_u32_e32 v240, 15, v240
	v_lshlrev_b32_e32 v213, 2, v240
	v_add_u32_e32 v240, 3, v241
	v_cmp_gt_u32_e64 s[46:47], 16, v240
	v_add_u32_e32 v240, 4, v235
	v_med3_i32 v240, v240, -15, 15
	v_add_u32_e32 v240, 15, v240
	v_lshlrev_b32_e32 v214, 2, v240
	v_add_u32_e32 v240, 4, v241
	v_cmp_gt_u32_e64 s[48:49], 16, v240
	v_add_u32_e32 v240, 5, v235
	v_med3_i32 v240, v240, -15, 15
	v_add_u32_e32 v240, 15, v240
	v_lshlrev_b32_e32 v215, 2, v240
	v_add_u32_e32 v240, 5, v241
	v_cmp_gt_u32_e64 s[50:51], 16, v240
	v_add_u32_e32 v240, 6, v235
	v_med3_i32 v240, v240, -15, 15
	v_add_u32_e32 v240, 15, v240
	v_lshlrev_b32_e32 v216, 2, v240
	v_add_u32_e32 v240, 6, v241
	v_cmp_gt_u32_e64 s[52:53], 16, v240
	v_add_u32_e32 v240, 7, v235
	v_med3_i32 v240, v240, -15, 15
	v_add_u32_e32 v240, 15, v240
	v_lshlrev_b32_e32 v217, 2, v240
	v_add_u32_e32 v240, 7, v241
	v_cmp_gt_u32_e64 s[54:55], 16, v240
	s_waitcnt lgkmcnt(0)
	s_mov_b32 s14, 0
	s_and_b32 s15, s7, 7
	s_bfe_u32 s16, s7, 0x50003
	s_lshr_b32 s17, s7, 8
	s_sub_i32 s18, s16, 4
	s_max_i32 s18, s18, 0
	s_min_i32 s18, s18, 24
	s_lshl_b32 s19, s17, 11
	s_lshl_b32 s20, s18, 6
	s_add_u32 s20, s20, s19
	s_add_u32 s20, s20, s8
	s_lshl_b32 s21, s16, 6
	s_add_u32 s21, s21, s19
	s_add_u32 s21, s21, s9
	s_lshl_b32 s22, s15, 7
	s_lshl_b32 s23, s20, 10
	s_add_u32 s23, s23, s22
	s_add_u32 s0, s10, 0x5200000
	s_addc_u32 s1, s11, 0
	s_add_u32 s0, s0, s23
	s_addc_u32 s1, s1, 0
	s_lshl_b32 s23, s21, 10
	s_add_u32 s23, s23, s22
	s_add_u32 s2, s10, 0x4200000
	s_addc_u32 s3, s11, 0
	s_add_u32 s2, s2, s23
	s_addc_u32 s3, s3, 0
	global_load_dwordx4 v[0:3], v221, s[2:3]
	global_load_dwordx4 v[4:7], v221, s[2:3] offset:64
	global_load_dwordx4 v[72:75], v218, s[0:1]
	global_load_dwordx4 v[76:79], v218, s[0:1] offset:64
	global_load_dwordx4 v[80:83], v219, s[0:1]
	global_load_dwordx4 v[84:87], v219, s[0:1] offset:64
	s_add_u32 s0, s0, 0x10000
	s_addc_u32 s1, s1, 0
	global_load_dwordx4 v[88:91], v218, s[0:1]
	global_load_dwordx4 v[92:95], v218, s[0:1] offset:64
	global_load_dwordx4 v[96:99], v219, s[0:1]
	global_load_dwordx4 v[100:103], v219, s[0:1] offset:64
	s_add_u32 s0, s0, 0x10000
	s_addc_u32 s1, s1, 0
	global_load_dwordx4 v[104:107], v218, s[0:1]
	global_load_dwordx4 v[108:111], v218, s[0:1] offset:64
	global_load_dwordx4 v[112:115], v219, s[0:1]
	global_load_dwordx4 v[116:119], v219, s[0:1] offset:64
	s_add_u32 s0, s0, 0x10000
	s_addc_u32 s1, s1, 0
	global_load_dwordx4 v[120:123], v218, s[0:1]
	global_load_dwordx4 v[124:127], v218, s[0:1] offset:64
	global_load_dwordx4 v[128:131], v219, s[0:1]
	global_load_dwordx4 v[132:135], v219, s[0:1] offset:64
	s_add_u32 s0, s0, 0x10000
	s_addc_u32 s1, s1, 0
	global_load_dwordx4 v[146:149], v218, s[0:1]
	global_load_dwordx4 v[150:153], v218, s[0:1] offset:64
	global_load_dwordx4 v[154:157], v219, s[0:1]
	global_load_dwordx4 v[158:161], v219, s[0:1] offset:64
	s_add_u32 s0, s0, 0x10000
	s_addc_u32 s1, s1, 0
	global_load_dwordx4 v[162:165], v218, s[0:1]
	global_load_dwordx4 v[166:169], v218, s[0:1] offset:64
	global_load_dwordx4 v[170:173], v219, s[0:1]
	global_load_dwordx4 v[174:177], v219, s[0:1] offset:64
	s_add_u32 s0, s0, 0x10000
	s_addc_u32 s1, s1, 0
.Lna_tile:
	s_and_b32 s15, s7, 7
	s_bfe_u32 s16, s7, 0x50003
	s_lshr_b32 s17, s7, 8
	s_sub_i32 s18, s16, 4
	s_max_i32 s18, s18, 0
	s_min_i32 s18, s18, 24
	s_lshl_b32 s19, s17, 11
	s_lshl_b32 s20, s18, 6
	s_add_u32 s20, s20, s19
	s_add_u32 s20, s20, s8
	s_lshl_b32 s21, s16, 6
	s_add_u32 s21, s21, s19
	s_add_u32 s21, s21, s9
	s_lshl_b32 s22, s15, 7
	s_lshl_b32 s23, s17, 3
	s_add_u32 s23, s23, s15
	s_lshl_b32 s23, s23, 18
	s_lshl_b32 s24, s5, 16
	s_add_u32 s23, s23, s24
	s_lshl_b32 s24, s18, 7
	s_add_u32 s23, s23, s24
	s_add_u32 s24, s10, 0x6200000
	s_addc_u32 s25, s11, 0
	s_add_u32 s24, s24, s23
	s_addc_u32 s25, s25, 0
	s_mul_i32 s23, s21, 0xc00
	s_add_u32 s23, s23, s22
	s_add_u32 s32, s10, 0xc200000
	s_addc_u32 s33, s11, 0
	s_add_u32 s32, s32, s23
	s_addc_u32 s33, s33, 0
	s_mul_i32 s23, s15, 465
	s_sub_i32 s34, s18, s16
	s_add_i32 s34, s34, 7
	s_mul_i32 s34, s34, 31
	s_add_u32 s23, s23, s34
	s_lshl_b32 s23, s23, 2
	s_add_u32 s34, s12, s23
	s_addc_u32 s35, s13, 0
	s_barrier
	global_load_dword v8, v210, s[34:35]
	global_load_dword v9, v211, s[34:35]
	global_load_dword v10, v212, s[34:35]
	global_load_dword v11, v213, s[34:35]
	global_load_dword v12, v214, s[34:35]
	global_load_dword v13, v215, s[34:35]
	global_load_dword v14, v216, s[34:35]
	global_load_dword v15, v217, s[34:35]
	global_load_dword v16, v210, s[34:35] offset:124
	global_load_dword v17, v211, s[34:35] offset:124
	global_load_dword v18, v212, s[34:35] offset:124
	global_load_dword v19, v213, s[34:35] offset:124
	global_load_dword v20, v214, s[34:35] offset:124
	global_load_dword v21, v215, s[34:35] offset:124
	global_load_dword v22, v216, s[34:35] offset:124
	global_load_dword v23, v217, s[34:35] offset:124
	global_load_dword v24, v210, s[34:35] offset:248
	global_load_dword v25, v211, s[34:35] offset:248
	global_load_dword v26, v212, s[34:35] offset:248
	global_load_dword v27, v213, s[34:35] offset:248
	global_load_dword v28, v214, s[34:35] offset:248
	global_load_dword v29, v215, s[34:35] offset:248
	global_load_dword v30, v216, s[34:35] offset:248
	global_load_dword v31, v217, s[34:35] offset:248
	global_load_dword v32, v210, s[34:35] offset:372
	global_load_dword v33, v211, s[34:35] offset:372
	global_load_dword v34, v212, s[34:35] offset:372
	global_load_dword v35, v213, s[34:35] offset:372
	global_load_dword v36, v214, s[34:35] offset:372
	global_load_dword v37, v215, s[34:35] offset:372
	global_load_dword v38, v216, s[34:35] offset:372
	global_load_dword v39, v217, s[34:35] offset:372
	global_load_dword v40, v210, s[34:35] offset:496
	global_load_dword v41, v211, s[34:35] offset:496
	global_load_dword v42, v212, s[34:35] offset:496
	global_load_dword v43, v213, s[34:35] offset:496
	global_load_dword v44, v214, s[34:35] offset:496
	global_load_dword v45, v215, s[34:35] offset:496
	global_load_dword v46, v216, s[34:35] offset:496
	global_load_dword v47, v217, s[34:35] offset:496
	global_load_dword v48, v210, s[34:35] offset:620
	global_load_dword v49, v211, s[34:35] offset:620
	global_load_dword v50, v212, s[34:35] offset:620
	global_load_dword v51, v213, s[34:35] offset:620
	global_load_dword v52, v214, s[34:35] offset:620
	global_load_dword v53, v215, s[34:35] offset:620
	global_load_dword v54, v216, s[34:35] offset:620
	global_load_dword v55, v217, s[34:35] offset:620
	global_load_dword v56, v210, s[34:35] offset:744
	global_load_dword v57, v211, s[34:35] offset:744
	global_load_dword v58, v212, s[34:35] offset:744
	global_load_dword v59, v213, s[34:35] offset:744
	global_load_dword v60, v214, s[34:35] offset:744
	global_load_dword v61, v215, s[34:35] offset:744
	global_load_dword v62, v216, s[34:35] offset:744
	global_load_dword v63, v217, s[34:35] offset:744
	global_load_dword v64, v210, s[34:35] offset:868
	global_load_dword v65, v211, s[34:35] offset:868
	global_load_dword v66, v212, s[34:35] offset:868
	global_load_dword v67, v213, s[34:35] offset:868
	global_load_dword v68, v214, s[34:35] offset:868
	global_load_dword v69, v215, s[34:35] offset:868
	global_load_dword v70, v216, s[34:35] offset:868
	global_load_dword v71, v217, s[34:35] offset:868
	s_mov_b32 s26, s39
	v_xor_b32_e32 v137, 0, v246
	s_mov_b32 m0, s26
	v_lshlrev_b32_e32 v137, 4, v137
	global_load_lds_dwordx4 v137, s[24:25]
	s_add_u32 s24, s24, 0x1000
	s_addc_u32 s25, s25, 0
	s_add_u32 s26, s26, 0x400
	v_xor_b32_e32 v137, 1, v246
	s_mov_b32 m0, s26
	v_lshlrev_b32_e32 v137, 4, v137
	global_load_lds_dwordx4 v137, s[24:25]
	s_add_u32 s24, s24, 0x1000
	s_addc_u32 s25, s25, 0
	s_add_u32 s26, s26, 0x400
	v_xor_b32_e32 v137, 2, v246
	s_mov_b32 m0, s26
	v_lshlrev_b32_e32 v137, 4, v137
	global_load_lds_dwordx4 v137, s[24:25]
	s_add_u32 s24, s24, 0x1000
	s_addc_u32 s25, s25, 0
	s_add_u32 s26, s26, 0x400
	v_xor_b32_e32 v137, 3, v246
	s_mov_b32 m0, s26
	v_lshlrev_b32_e32 v137, 4, v137
	global_load_lds_dwordx4 v137, s[24:25]
	s_add_u32 s24, s24, 0x1000
	s_addc_u32 s25, s25, 0
	s_add_u32 s26, s26, 0x400
	v_xor_b32_e32 v137, 4, v246
	s_mov_b32 m0, s26
	v_lshlrev_b32_e32 v137, 4, v137
	global_load_lds_dwordx4 v137, s[24:25]
	s_add_u32 s24, s24, 0x1000
	s_addc_u32 s25, s25, 0
	s_add_u32 s26, s26, 0x400
	v_xor_b32_e32 v137, 5, v246
	s_mov_b32 m0, s26
	v_lshlrev_b32_e32 v137, 4, v137
	global_load_lds_dwordx4 v137, s[24:25]
	s_add_u32 s24, s24, 0x1000
	s_addc_u32 s25, s25, 0
	s_add_u32 s26, s26, 0x400
	v_xor_b32_e32 v137, 6, v246
	s_mov_b32 m0, s26
	v_lshlrev_b32_e32 v137, 4, v137
	global_load_lds_dwordx4 v137, s[24:25]
	s_add_u32 s24, s24, 0x1000
	s_addc_u32 s25, s25, 0
	s_add_u32 s26, s26, 0x400
	v_xor_b32_e32 v137, 7, v246
	s_mov_b32 m0, s26
	v_lshlrev_b32_e32 v137, 4, v137
	global_load_lds_dwordx4 v137, s[24:25]
	s_add_u32 s24, s24, 0x1000
	s_addc_u32 s25, s25, 0
	s_add_u32 s26, s26, 0x400
	v_xor_b32_e32 v137, 8, v246
	s_mov_b32 m0, s26
	v_lshlrev_b32_e32 v137, 4, v137
	global_load_lds_dwordx4 v137, s[24:25]
	s_add_u32 s24, s24, 0x1000
	s_addc_u32 s25, s25, 0
	s_add_u32 s26, s26, 0x400
	v_xor_b32_e32 v137, 9, v246
	s_mov_b32 m0, s26
	v_lshlrev_b32_e32 v137, 4, v137
	global_load_lds_dwordx4 v137, s[24:25]
	s_add_u32 s24, s24, 0x1000
	s_addc_u32 s25, s25, 0
	s_add_u32 s26, s26, 0x400
	v_xor_b32_e32 v137, 10, v246
	s_mov_b32 m0, s26
	v_lshlrev_b32_e32 v137, 4, v137
	global_load_lds_dwordx4 v137, s[24:25]
	s_add_u32 s24, s24, 0x1000
	s_addc_u32 s25, s25, 0
	s_add_u32 s26, s26, 0x400
	v_xor_b32_e32 v137, 11, v246
	s_mov_b32 m0, s26
	v_lshlrev_b32_e32 v137, 4, v137
	global_load_lds_dwordx4 v137, s[24:25]
	s_add_u32 s24, s24, 0x1000
	s_addc_u32 s25, s25, 0
	s_add_u32 s26, s26, 0x400
	v_xor_b32_e32 v137, 12, v246
	s_mov_b32 m0, s26
	v_lshlrev_b32_e32 v137, 4, v137
	global_load_lds_dwordx4 v137, s[24:25]
	s_add_u32 s24, s24, 0x1000
	s_addc_u32 s25, s25, 0
	s_add_u32 s26, s26, 0x400
	v_xor_b32_e32 v137, 13, v246
	s_mov_b32 m0, s26
	v_lshlrev_b32_e32 v137, 4, v137
	global_load_lds_dwordx4 v137, s[24:25]
	s_add_u32 s24, s24, 0x1000
	s_addc_u32 s25, s25, 0
	s_add_u32 s26, s26, 0x400
	v_xor_b32_e32 v137, 14, v246
	s_mov_b32 m0, s26
	v_lshlrev_b32_e32 v137, 4, v137
	global_load_lds_dwordx4 v137, s[24:25]
	s_add_u32 s24, s24, 0x1000
	s_addc_u32 s25, s25, 0
	s_add_u32 s26, s26, 0x400
	v_xor_b32_e32 v137, 15, v246
	s_mov_b32 m0, s26
	v_lshlrev_b32_e32 v137, 4, v137
	global_load_lds_dwordx4 v137, s[24:25]
	s_add_u32 s24, s24, 0x1000
	s_addc_u32 s25, s25, 0
	s_add_u32 s26, s26, 0x400
	v_mov_b32_e32 v178, 0
	v_mov_b32_e32 v179, 0
	v_mov_b32_e32 v180, 0
	v_mov_b32_e32 v181, 0
	v_mov_b32_e32 v182, 0
	v_mov_b32_e32 v183, 0
	v_mov_b32_e32 v184, 0
	v_mov_b32_e32 v185, 0
	v_mov_b32_e32 v186, 0
	v_mov_b32_e32 v187, 0
	v_mov_b32_e32 v188, 0
	v_mov_b32_e32 v189, 0
	v_mov_b32_e32 v190, 0
	v_mov_b32_e32 v191, 0
	v_mov_b32_e32 v192, 0
	v_mov_b32_e32 v193, 0
	s_waitcnt vmcnt(63)
	v_mfma_f32_16x16x32_bf16 v[194:197], v[72:75], v[0:3], 0
	v_mfma_f32_16x16x32_bf16 v[198:201], v[80:83], v[0:3], 0
	v_mfma_f32_16x16x32_bf16 v[194:197], v[76:79], v[4:7], v[194:197]
	v_mfma_f32_16x16x32_bf16 v[198:201], v[84:87], v[4:7], v[198:201]
	global_load_dwordx4 v[72:75], v218, s[0:1]
	global_load_dwordx4 v[76:79], v218, s[0:1] offset:64
	global_load_dwordx4 v[80:83], v219, s[0:1]
	global_load_dwordx4 v[84:87], v219, s[0:1] offset:64
	s_add_u32 s0, s0, 0x10000
	s_addc_u32 s1, s1, 0
	s_waitcnt vmcnt(63)
	v_mfma_f32_16x16x32_bf16 v[202:205], v[88:91], v[0:3], 0
	v_mfma_f32_16x16x32_bf16 v[206:209], v[96:99], v[0:3], 0
	v_mfma_f32_16x16x32_bf16 v[202:205], v[92:95], v[4:7], v[202:205]
	v_mfma_f32_16x16x32_bf16 v[206:209], v[100:103], v[4:7], v[206:209]
	global_load_dwordx4 v[88:91], v218, s[0:1]
	global_load_dwordx4 v[92:95], v218, s[0:1] offset:64
	global_load_dwordx4 v[96:99], v219, s[0:1]
	global_load_dwordx4 v[100:103], v219, s[0:1] offset:64
	s_add_u32 s0, s0, 0x10000
	s_addc_u32 s1, s1, 0
	s_waitcnt vmcnt(63)
	v_fmamk_f32 v235, v8, 0x3fb8aa3b, v194
	v_mov_b32_e32 v8, 0xff800000
	v_cndmask_b32_e64 v8, v8, v235, s[40:41]
	v_fmamk_f32 v235, v9, 0x3fb8aa3b, v195
	v_mov_b32_e32 v9, 0xff800000
	v_cndmask_b32_e64 v9, v9, v235, s[42:43]
	v_fmamk_f32 v235, v10, 0x3fb8aa3b, v196
	v_mov_b32_e32 v10, 0xff800000
	v_cndmask_b32_e64 v10, v10, v235, s[44:45]
	v_fmamk_f32 v235, v11, 0x3fb8aa3b, v197
	v_mov_b32_e32 v11, 0xff800000
	v_cndmask_b32_e64 v11, v11, v235, s[46:47]
	v_fmamk_f32 v235, v12, 0x3fb8aa3b, v198
	v_mov_b32_e32 v12, 0xff800000
	v_cndmask_b32_e64 v12, v12, v235, s[48:49]
	v_fmamk_f32 v235, v13, 0x3fb8aa3b, v199
	v_mov_b32_e32 v13, 0xff800000
	v_cndmask_b32_e64 v13, v13, v235, s[50:51]
	v_fmamk_f32 v235, v14, 0x3fb8aa3b, v200
	v_mov_b32_e32 v14, 0xff800000
	v_cndmask_b32_e64 v14, v14, v235, s[52:53]
	v_fmamk_f32 v235, v15, 0x3fb8aa3b, v201
	v_mov_b32_e32 v15, 0xff800000
	v_cndmask_b32_e64 v15, v15, v235, s[54:55]
	s_waitcnt vmcnt(63)
	v_mfma_f32_16x16x32_bf16 v[194:197], v[104:107], v[0:3], 0
	v_mfma_f32_16x16x32_bf16 v[198:201], v[112:115], v[0:3], 0
	v_mfma_f32_16x16x32_bf16 v[194:197], v[108:111], v[4:7], v[194:197]
	v_mfma_f32_16x16x32_bf16 v[198:201], v[116:119], v[4:7], v[198:201]
	s_waitcnt vmcnt(63)
	v_fmamk_f32 v235, v16, 0x3fb8aa3b, v202
	v_mov_b32_e32 v16, 0xff800000
	v_cndmask_b32_e64 v16, v16, v235, s[40:41]
	v_fmamk_f32 v235, v17, 0x3fb8aa3b, v203
	v_mov_b32_e32 v17, 0xff800000
	v_cndmask_b32_e64 v17, v17, v235, s[42:43]
	v_fmamk_f32 v235, v18, 0x3fb8aa3b, v204
	v_mov_b32_e32 v18, 0xff800000
	v_cndmask_b32_e64 v18, v18, v235, s[44:45]
	v_fmamk_f32 v235, v19, 0x3fb8aa3b, v205
	v_mov_b32_e32 v19, 0xff800000
	v_cndmask_b32_e64 v19, v19, v235, s[46:47]
	v_fmamk_f32 v235, v20, 0x3fb8aa3b, v206
	v_mov_b32_e32 v20, 0xff800000
	v_cndmask_b32_e64 v20, v20, v235, s[48:49]
	v_fmamk_f32 v235, v21, 0x3fb8aa3b, v207
	v_mov_b32_e32 v21, 0xff800000
	v_cndmask_b32_e64 v21, v21, v235, s[50:51]
	v_fmamk_f32 v235, v22, 0x3fb8aa3b, v208
	v_mov_b32_e32 v22, 0xff800000
	v_cndmask_b32_e64 v22, v22, v235, s[52:53]
	v_fmamk_f32 v235, v23, 0x3fb8aa3b, v209
	v_mov_b32_e32 v23, 0xff800000
	v_cndmask_b32_e64 v23, v23, v235, s[54:55]
	s_waitcnt vmcnt(63)
	v_mfma_f32_16x16x32_bf16 v[202:205], v[120:123], v[0:3], 0
	v_mfma_f32_16x16x32_bf16 v[206:209], v[128:131], v[0:3], 0
	v_mfma_f32_16x16x32_bf16 v[202:205], v[124:127], v[4:7], v[202:205]
	v_mfma_f32_16x16x32_bf16 v[206:209], v[132:135], v[4:7], v[206:209]
	s_waitcnt vmcnt(63)
	v_fmamk_f32 v235, v24, 0x3fb8aa3b, v194
	v_mov_b32_e32 v24, 0xff800000
	v_cndmask_b32_e64 v24, v24, v235, s[40:41]
	v_fmamk_f32 v235, v25, 0x3fb8aa3b, v195
	v_mov_b32_e32 v25, 0xff800000
	v_cndmask_b32_e64 v25, v25, v235, s[42:43]
	v_fmamk_f32 v235, v26, 0x3fb8aa3b, v196
	v_mov_b32_e32 v26, 0xff800000
	v_cndmask_b32_e64 v26, v26, v235, s[44:45]
	v_fmamk_f32 v235, v27, 0x3fb8aa3b, v197
	v_mov_b32_e32 v27, 0xff800000
	v_cndmask_b32_e64 v27, v27, v235, s[46:47]
	v_fmamk_f32 v235, v28, 0x3fb8aa3b, v198
	v_mov_b32_e32 v28, 0xff800000
	v_cndmask_b32_e64 v28, v28, v235, s[48:49]
	v_fmamk_f32 v235, v29, 0x3fb8aa3b, v199
	v_mov_b32_e32 v29, 0xff800000
	v_cndmask_b32_e64 v29, v29, v235, s[50:51]
	v_fmamk_f32 v235, v30, 0x3fb8aa3b, v200
	v_mov_b32_e32 v30, 0xff800000
	v_cndmask_b32_e64 v30, v30, v235, s[52:53]
	v_fmamk_f32 v235, v31, 0x3fb8aa3b, v201
	v_mov_b32_e32 v31, 0xff800000
	v_cndmask_b32_e64 v31, v31, v235, s[54:55]
	s_waitcnt vmcnt(63)
	v_mfma_f32_16x16x32_bf16 v[194:197], v[146:149], v[0:3], 0
	v_mfma_f32_16x16x32_bf16 v[198:201], v[154:157], v[0:3], 0
	v_mfma_f32_16x16x32_bf16 v[194:197], v[150:153], v[4:7], v[194:197]
	v_mfma_f32_16x16x32_bf16 v[198:201], v[158:161], v[4:7], v[198:201]
	s_waitcnt vmcnt(56)
	v_fmamk_f32 v235, v32, 0x3fb8aa3b, v202
	v_mov_b32_e32 v32, 0xff800000
	v_cndmask_b32_e64 v32, v32, v235, s[40:41]
	v_fmamk_f32 v235, v33, 0x3fb8aa3b, v203
	v_mov_b32_e32 v33, 0xff800000
	v_cndmask_b32_e64 v33, v33, v235, s[42:43]
	v_fmamk_f32 v235, v34, 0x3fb8aa3b, v204
	v_mov_b32_e32 v34, 0xff800000
	v_cndmask_b32_e64 v34, v34, v235, s[44:45]
	v_fmamk_f32 v235, v35, 0x3fb8aa3b, v205
	v_mov_b32_e32 v35, 0xff800000
	v_cndmask_b32_e64 v35, v35, v235, s[46:47]
	v_fmamk_f32 v235, v36, 0x3fb8aa3b, v206
	v_mov_b32_e32 v36, 0xff800000
	v_cndmask_b32_e64 v36, v36, v235, s[48:49]
	v_fmamk_f32 v235, v37, 0x3fb8aa3b, v207
	v_mov_b32_e32 v37, 0xff800000
	v_cndmask_b32_e64 v37, v37, v235, s[50:51]
	v_fmamk_f32 v235, v38, 0x3fb8aa3b, v208
	v_mov_b32_e32 v38, 0xff800000
	v_cndmask_b32_e64 v38, v38, v235, s[52:53]
	v_fmamk_f32 v235, v39, 0x3fb8aa3b, v209
	v_mov_b32_e32 v39, 0xff800000
	v_cndmask_b32_e64 v39, v39, v235, s[54:55]
	s_waitcnt vmcnt(63)
	v_mfma_f32_16x16x32_bf16 v[202:205], v[162:165], v[0:3], 0
	v_mfma_f32_16x16x32_bf16 v[206:209], v[170:173], v[0:3], 0
	v_mfma_f32_16x16x32_bf16 v[202:205], v[166:169], v[4:7], v[202:205]
	v_mfma_f32_16x16x32_bf16 v[206:209], v[174:177], v[4:7], v[206:209]
	s_waitcnt vmcnt(48)
	v_fmamk_f32 v235, v40, 0x3fb8aa3b, v194
	v_mov_b32_e32 v40, 0xff800000
	v_cndmask_b32_e64 v40, v40, v235, s[40:41]
	v_fmamk_f32 v235, v41, 0x3fb8aa3b, v195
	v_mov_b32_e32 v41, 0xff800000
	v_cndmask_b32_e64 v41, v41, v235, s[42:43]
	v_fmamk_f32 v235, v42, 0x3fb8aa3b, v196
	v_mov_b32_e32 v42, 0xff800000
	v_cndmask_b32_e64 v42, v42, v235, s[44:45]
	v_fmamk_f32 v235, v43, 0x3fb8aa3b, v197
	v_mov_b32_e32 v43, 0xff800000
	v_cndmask_b32_e64 v43, v43, v235, s[46:47]
	v_fmamk_f32 v235, v44, 0x3fb8aa3b, v198
	v_mov_b32_e32 v44, 0xff800000
	v_cndmask_b32_e64 v44, v44, v235, s[48:49]
	v_fmamk_f32 v235, v45, 0x3fb8aa3b, v199
	v_mov_b32_e32 v45, 0xff800000
	v_cndmask_b32_e64 v45, v45, v235, s[50:51]
	v_fmamk_f32 v235, v46, 0x3fb8aa3b, v200
	v_mov_b32_e32 v46, 0xff800000
	v_cndmask_b32_e64 v46, v46, v235, s[52:53]
	v_fmamk_f32 v235, v47, 0x3fb8aa3b, v201
	v_mov_b32_e32 v47, 0xff800000
	v_cndmask_b32_e64 v47, v47, v235, s[54:55]
	s_waitcnt vmcnt(4)
	v_mfma_f32_16x16x32_bf16 v[194:197], v[72:75], v[0:3], 0
	v_mfma_f32_16x16x32_bf16 v[198:201], v[80:83], v[0:3], 0
	v_mfma_f32_16x16x32_bf16 v[194:197], v[76:79], v[4:7], v[194:197]
	v_mfma_f32_16x16x32_bf16 v[198:201], v[84:87], v[4:7], v[198:201]
	s_waitcnt vmcnt(40)
	v_fmamk_f32 v235, v48, 0x3fb8aa3b, v202
	v_mov_b32_e32 v48, 0xff800000
	v_cndmask_b32_e64 v48, v48, v235, s[40:41]
	v_fmamk_f32 v235, v49, 0x3fb8aa3b, v203
	v_mov_b32_e32 v49, 0xff800000
	v_cndmask_b32_e64 v49, v49, v235, s[42:43]
	v_fmamk_f32 v235, v50, 0x3fb8aa3b, v204
	v_mov_b32_e32 v50, 0xff800000
	v_cndmask_b32_e64 v50, v50, v235, s[44:45]
	v_fmamk_f32 v235, v51, 0x3fb8aa3b, v205
	v_mov_b32_e32 v51, 0xff800000
	v_cndmask_b32_e64 v51, v51, v235, s[46:47]
	v_fmamk_f32 v235, v52, 0x3fb8aa3b, v206
	v_mov_b32_e32 v52, 0xff800000
	v_cndmask_b32_e64 v52, v52, v235, s[48:49]
	v_fmamk_f32 v235, v53, 0x3fb8aa3b, v207
	v_mov_b32_e32 v53, 0xff800000
	v_cndmask_b32_e64 v53, v53, v235, s[50:51]
	v_fmamk_f32 v235, v54, 0x3fb8aa3b, v208
	v_mov_b32_e32 v54, 0xff800000
	v_cndmask_b32_e64 v54, v54, v235, s[52:53]
	v_fmamk_f32 v235, v55, 0x3fb8aa3b, v209
	v_mov_b32_e32 v55, 0xff800000
	v_cndmask_b32_e64 v55, v55, v235, s[54:55]
	s_waitcnt vmcnt(0)
	v_mfma_f32_16x16x32_bf16 v[202:205], v[88:91], v[0:3], 0
	v_mfma_f32_16x16x32_bf16 v[206:209], v[96:99], v[0:3], 0
	v_mfma_f32_16x16x32_bf16 v[202:205], v[92:95], v[4:7], v[202:205]
	v_mfma_f32_16x16x32_bf16 v[206:209], v[100:103], v[4:7], v[206:209]
	s_waitcnt vmcnt(32)
	v_fmamk_f32 v235, v56, 0x3fb8aa3b, v194
	v_mov_b32_e32 v56, 0xff800000
	v_cndmask_b32_e64 v56, v56, v235, s[40:41]
	v_fmamk_f32 v235, v57, 0x3fb8aa3b, v195
	v_mov_b32_e32 v57, 0xff800000
	v_cndmask_b32_e64 v57, v57, v235, s[42:43]
	v_fmamk_f32 v235, v58, 0x3fb8aa3b, v196
	v_mov_b32_e32 v58, 0xff800000
	v_cndmask_b32_e64 v58, v58, v235, s[44:45]
	v_fmamk_f32 v235, v59, 0x3fb8aa3b, v197
	v_mov_b32_e32 v59, 0xff800000
	v_cndmask_b32_e64 v59, v59, v235, s[46:47]
	v_fmamk_f32 v235, v60, 0x3fb8aa3b, v198
	v_mov_b32_e32 v60, 0xff800000
	v_cndmask_b32_e64 v60, v60, v235, s[48:49]
	v_fmamk_f32 v235, v61, 0x3fb8aa3b, v199
	v_mov_b32_e32 v61, 0xff800000
	v_cndmask_b32_e64 v61, v61, v235, s[50:51]
	v_fmamk_f32 v235, v62, 0x3fb8aa3b, v200
	v_mov_b32_e32 v62, 0xff800000
	v_cndmask_b32_e64 v62, v62, v235, s[52:53]
	v_fmamk_f32 v235, v63, 0x3fb8aa3b, v201
	v_mov_b32_e32 v63, 0xff800000
	v_cndmask_b32_e64 v63, v63, v235, s[54:55]
	s_nop 7
	s_waitcnt vmcnt(24)
	v_fmamk_f32 v235, v64, 0x3fb8aa3b, v202
	v_mov_b32_e32 v64, 0xff800000
	v_cndmask_b32_e64 v64, v64, v235, s[40:41]
	v_fmamk_f32 v235, v65, 0x3fb8aa3b, v203
	v_mov_b32_e32 v65, 0xff800000
	v_cndmask_b32_e64 v65, v65, v235, s[42:43]
	v_fmamk_f32 v235, v66, 0x3fb8aa3b, v204
	v_mov_b32_e32 v66, 0xff800000
	v_cndmask_b32_e64 v66, v66, v235, s[44:45]
	v_fmamk_f32 v235, v67, 0x3fb8aa3b, v205
	v_mov_b32_e32 v67, 0xff800000
	v_cndmask_b32_e64 v67, v67, v235, s[46:47]
	v_fmamk_f32 v235, v68, 0x3fb8aa3b, v206
	v_mov_b32_e32 v68, 0xff800000
	v_cndmask_b32_e64 v68, v68, v235, s[48:49]
	v_fmamk_f32 v235, v69, 0x3fb8aa3b, v207
	v_mov_b32_e32 v69, 0xff800000
	v_cndmask_b32_e64 v69, v69, v235, s[50:51]
	v_fmamk_f32 v235, v70, 0x3fb8aa3b, v208
	v_mov_b32_e32 v70, 0xff800000
	v_cndmask_b32_e64 v70, v70, v235, s[52:53]
	v_fmamk_f32 v235, v71, 0x3fb8aa3b, v209
	v_mov_b32_e32 v71, 0xff800000
	v_cndmask_b32_e64 v71, v71, v235, s[54:55]
	s_cmp_lt_u32 s14, 3
	s_cbranch_scc0 .Lna_nopf
	s_add_u32 s7, s7, 0x200
	s_and_b32 s15, s7, 7
	s_bfe_u32 s16, s7, 0x50003
	s_lshr_b32 s17, s7, 8
	s_sub_i32 s18, s16, 4
	s_max_i32 s18, s18, 0
	s_min_i32 s18, s18, 24
	s_lshl_b32 s19, s17, 11
	s_lshl_b32 s20, s18, 6
	s_add_u32 s20, s20, s19
	s_add_u32 s20, s20, s8
	s_lshl_b32 s21, s16, 6
	s_add_u32 s21, s21, s19
	s_add_u32 s21, s21, s9
	s_lshl_b32 s22, s15, 7
	s_lshl_b32 s23, s20, 10
	s_add_u32 s23, s23, s22
	s_add_u32 s0, s10, 0x5200000
	s_addc_u32 s1, s11, 0
	s_add_u32 s0, s0, s23
	s_addc_u32 s1, s1, 0
	s_lshl_b32 s23, s21, 10
	s_add_u32 s23, s23, s22
	s_add_u32 s2, s10, 0x4200000
	s_addc_u32 s3, s11, 0
	s_add_u32 s2, s2, s23
	s_addc_u32 s3, s3, 0
	global_load_dwordx4 v[0:3], v221, s[2:3]
	global_load_dwordx4 v[4:7], v221, s[2:3] offset:64
	global_load_dwordx4 v[72:75], v218, s[0:1]
	global_load_dwordx4 v[76:79], v218, s[0:1] offset:64
	global_load_dwordx4 v[80:83], v219, s[0:1]
	global_load_dwordx4 v[84:87], v219, s[0:1] offset:64
	s_add_u32 s0, s0, 0x10000
	s_addc_u32 s1, s1, 0
	global_load_dwordx4 v[88:91], v218, s[0:1]
	global_load_dwordx4 v[92:95], v218, s[0:1] offset:64
	global_load_dwordx4 v[96:99], v219, s[0:1]
	global_load_dwordx4 v[100:103], v219, s[0:1] offset:64
	s_add_u32 s0, s0, 0x10000
	s_addc_u32 s1, s1, 0
	global_load_dwordx4 v[104:107], v218, s[0:1]
	global_load_dwordx4 v[108:111], v218, s[0:1] offset:64
	global_load_dwordx4 v[112:115], v219, s[0:1]
	global_load_dwordx4 v[116:119], v219, s[0:1] offset:64
	s_add_u32 s0, s0, 0x10000
	s_addc_u32 s1, s1, 0
	global_load_dwordx4 v[120:123], v218, s[0:1]
	global_load_dwordx4 v[124:127], v218, s[0:1] offset:64
	global_load_dwordx4 v[128:131], v219, s[0:1]
	global_load_dwordx4 v[132:135], v219, s[0:1] offset:64
	s_add_u32 s0, s0, 0x10000
	s_addc_u32 s1, s1, 0
	global_load_dwordx4 v[146:149], v218, s[0:1]
	global_load_dwordx4 v[150:153], v218, s[0:1] offset:64
	global_load_dwordx4 v[154:157], v219, s[0:1]
	global_load_dwordx4 v[158:161], v219, s[0:1] offset:64
	s_add_u32 s0, s0, 0x10000
	s_addc_u32 s1, s1, 0
	global_load_dwordx4 v[162:165], v218, s[0:1]
	global_load_dwordx4 v[166:169], v218, s[0:1] offset:64
	global_load_dwordx4 v[170:173], v219, s[0:1]
	global_load_dwordx4 v[174:177], v219, s[0:1] offset:64
	s_add_u32 s0, s0, 0x10000
	s_addc_u32 s1, s1, 0
.Lna_nopf:
	v_max3_f32 v233, v8, v9, v10
	v_max_f32_e32 v233, v233, v11
	v_max_f32_e32 v233, v233, v12
	v_max_f32_e32 v233, v233, v13
	v_max_f32_e32 v233, v233, v14
	v_max_f32_e32 v233, v233, v15
	v_max_f32_e32 v233, v233, v16
	v_max_f32_e32 v233, v233, v17
	v_max_f32_e32 v233, v233, v18
	v_max_f32_e32 v233, v233, v19
	v_max_f32_e32 v233, v233, v20
	v_max_f32_e32 v233, v233, v21
	v_max_f32_e32 v233, v233, v22
	v_max_f32_e32 v233, v233, v23
	v_max_f32_e32 v233, v233, v24
	v_max_f32_e32 v233, v233, v25
	v_max_f32_e32 v233, v233, v26
	v_max_f32_e32 v233, v233, v27
	v_max_f32_e32 v233, v233, v28
	v_max_f32_e32 v233, v233, v29
	v_max_f32_e32 v233, v233, v30
	v_max_f32_e32 v233, v233, v31
	v_max_f32_e32 v233, v233, v32
	v_max_f32_e32 v233, v233, v33
	v_max_f32_e32 v233, v233, v34
	v_max_f32_e32 v233, v233, v35
	v_max_f32_e32 v233, v233, v36
	v_max_f32_e32 v233, v233, v37
	v_max_f32_e32 v233, v233, v38
	v_max_f32_e32 v233, v233, v39
	v_max_f32_e32 v233, v233, v40
	v_max_f32_e32 v233, v233, v41
	v_max_f32_e32 v233, v233, v42
	v_max_f32_e32 v233, v233, v43
	v_max_f32_e32 v233, v233, v44
	v_max_f32_e32 v233, v233, v45
	v_max_f32_e32 v233, v233, v46
	v_max_f32_e32 v233, v233, v47
	v_max_f32_e32 v233, v233, v48
	v_max_f32_e32 v233, v233, v49
	v_max_f32_e32 v233, v233, v50
	v_max_f32_e32 v233, v233, v51
	v_max_f32_e32 v233, v233, v52
	v_max_f32_e32 v233, v233, v53
	v_max_f32_e32 v233, v233, v54
	v_max_f32_e32 v233, v233, v55
	v_max_f32_e32 v233, v233, v56
	v_max_f32_e32 v233, v233, v57
	v_max_f32_e32 v233, v233, v58
	v_max_f32_e32 v233, v233, v59
	v_max_f32_e32 v233, v233, v60
	v_max_f32_e32 v233, v233, v61
	v_max_f32_e32 v233, v233, v62
	v_max_f32_e32 v233, v233, v63
	v_max_f32_e32 v233, v233, v64
	v_max_f32_e32 v233, v233, v65
	v_max_f32_e32 v233, v233, v66
	v_max_f32_e32 v233, v233, v67
	v_max_f32_e32 v233, v233, v68
	v_max_f32_e32 v233, v233, v69
	v_max_f32_e32 v233, v233, v70
	v_max_f32_e32 v233, v233, v71
	ds_bpermute_b32 v235, v223, v233
	s_waitcnt lgkmcnt(0)
	v_max_f32_e32 v233, v233, v235
	ds_bpermute_b32 v235, v232, v233
	s_waitcnt lgkmcnt(0)
	v_max_f32_e32 v233, v233, v235
	v_mov_b32_e32 v234, 0
	v_sub_f32_e32 v8, v8, v233
	v_exp_f32_e32 v8, v8
	v_sub_f32_e32 v9, v9, v233
	v_add_f32_e32 v234, v234, v8
	v_exp_f32_e32 v9, v9
	v_sub_f32_e32 v10, v10, v233
	v_add_f32_e32 v234, v234, v9
	v_exp_f32_e32 v10, v10
	v_sub_f32_e32 v11, v11, v233
	v_add_f32_e32 v234, v234, v10
	v_exp_f32_e32 v11, v11
	v_sub_f32_e32 v12, v12, v233
	v_add_f32_e32 v234, v234, v11
	v_exp_f32_e32 v12, v12
	v_sub_f32_e32 v13, v13, v233
	v_add_f32_e32 v234, v234, v12
	v_exp_f32_e32 v13, v13
	v_sub_f32_e32 v14, v14, v233
	v_add_f32_e32 v234, v234, v13
	v_exp_f32_e32 v14, v14
	v_sub_f32_e32 v15, v15, v233
	v_add_f32_e32 v234, v234, v14
	v_exp_f32_e32 v15, v15
	v_sub_f32_e32 v16, v16, v233
	v_add_f32_e32 v234, v234, v15
	v_exp_f32_e32 v16, v16
	v_sub_f32_e32 v17, v17, v233
	v_add_f32_e32 v234, v234, v16
	v_exp_f32_e32 v17, v17
	v_sub_f32_e32 v18, v18, v233
	v_add_f32_e32 v234, v234, v17
	v_exp_f32_e32 v18, v18
	v_sub_f32_e32 v19, v19, v233
	v_add_f32_e32 v234, v234, v18
	v_exp_f32_e32 v19, v19
	v_sub_f32_e32 v20, v20, v233
	v_add_f32_e32 v234, v234, v19
	v_exp_f32_e32 v20, v20
	v_sub_f32_e32 v21, v21, v233
	v_add_f32_e32 v234, v234, v20
	v_exp_f32_e32 v21, v21
	v_sub_f32_e32 v22, v22, v233
	v_add_f32_e32 v234, v234, v21
	v_exp_f32_e32 v22, v22
	v_sub_f32_e32 v23, v23, v233
	v_add_f32_e32 v234, v234, v22
	v_exp_f32_e32 v23, v23
	v_sub_f32_e32 v24, v24, v233
	v_add_f32_e32 v234, v234, v23
	v_exp_f32_e32 v24, v24
	v_sub_f32_e32 v25, v25, v233
	v_add_f32_e32 v234, v234, v24
	v_exp_f32_e32 v25, v25
	v_sub_f32_e32 v26, v26, v233
	v_add_f32_e32 v234, v234, v25
	v_exp_f32_e32 v26, v26
	v_sub_f32_e32 v27, v27, v233
	v_add_f32_e32 v234, v234, v26
	v_exp_f32_e32 v27, v27
	v_sub_f32_e32 v28, v28, v233
	v_add_f32_e32 v234, v234, v27
	v_exp_f32_e32 v28, v28
	v_sub_f32_e32 v29, v29, v233
	v_add_f32_e32 v234, v234, v28
	v_exp_f32_e32 v29, v29
	v_sub_f32_e32 v30, v30, v233
	v_add_f32_e32 v234, v234, v29
	v_exp_f32_e32 v30, v30
	v_sub_f32_e32 v31, v31, v233
	v_add_f32_e32 v234, v234, v30
	v_exp_f32_e32 v31, v31
	v_sub_f32_e32 v32, v32, v233
	v_add_f32_e32 v234, v234, v31
	v_exp_f32_e32 v32, v32
	v_sub_f32_e32 v33, v33, v233
	v_add_f32_e32 v234, v234, v32
	v_exp_f32_e32 v33, v33
	v_sub_f32_e32 v34, v34, v233
	v_add_f32_e32 v234, v234, v33
	v_exp_f32_e32 v34, v34
	v_sub_f32_e32 v35, v35, v233
	v_add_f32_e32 v234, v234, v34
	v_exp_f32_e32 v35, v35
	v_sub_f32_e32 v36, v36, v233
	v_add_f32_e32 v234, v234, v35
	v_exp_f32_e32 v36, v36
	v_sub_f32_e32 v37, v37, v233
	v_add_f32_e32 v234, v234, v36
	v_exp_f32_e32 v37, v37
	v_sub_f32_e32 v38, v38, v233
	v_add_f32_e32 v234, v234, v37
	v_exp_f32_e32 v38, v38
	v_sub_f32_e32 v39, v39, v233
	v_add_f32_e32 v234, v234, v38
	v_exp_f32_e32 v39, v39
	v_sub_f32_e32 v40, v40, v233
	v_add_f32_e32 v234, v234, v39
	v_exp_f32_e32 v40, v40
	v_sub_f32_e32 v41, v41, v233
	v_add_f32_e32 v234, v234, v40
	v_exp_f32_e32 v41, v41
	v_sub_f32_e32 v42, v42, v233
	v_add_f32_e32 v234, v234, v41
	v_exp_f32_e32 v42, v42
	v_sub_f32_e32 v43, v43, v233
	v_add_f32_e32 v234, v234, v42
	v_exp_f32_e32 v43, v43
	v_sub_f32_e32 v44, v44, v233
	v_add_f32_e32 v234, v234, v43
	v_exp_f32_e32 v44, v44
	v_sub_f32_e32 v45, v45, v233
	v_add_f32_e32 v234, v234, v44
	v_exp_f32_e32 v45, v45
	v_sub_f32_e32 v46, v46, v233
	v_add_f32_e32 v234, v234, v45
	v_exp_f32_e32 v46, v46
	v_sub_f32_e32 v47, v47, v233
	v_add_f32_e32 v234, v234, v46
	v_exp_f32_e32 v47, v47
	v_sub_f32_e32 v48, v48, v233
	v_add_f32_e32 v234, v234, v47
	v_exp_f32_e32 v48, v48
	v_sub_f32_e32 v49, v49, v233
	v_add_f32_e32 v234, v234, v48
	v_exp_f32_e32 v49, v49
	v_sub_f32_e32 v50, v50, v233
	v_add_f32_e32 v234, v234, v49
	v_exp_f32_e32 v50, v50
	v_sub_f32_e32 v51, v51, v233
	v_add_f32_e32 v234, v234, v50
	v_exp_f32_e32 v51, v51
	v_sub_f32_e32 v52, v52, v233
	v_add_f32_e32 v234, v234, v51
	v_exp_f32_e32 v52, v52
	v_sub_f32_e32 v53, v53, v233
	v_add_f32_e32 v234, v234, v52
	v_exp_f32_e32 v53, v53
	v_sub_f32_e32 v54, v54, v233
	v_add_f32_e32 v234, v234, v53
	v_exp_f32_e32 v54, v54
	v_sub_f32_e32 v55, v55, v233
	v_add_f32_e32 v234, v234, v54
	v_exp_f32_e32 v55, v55
	v_sub_f32_e32 v56, v56, v233
	v_add_f32_e32 v234, v234, v55
	v_exp_f32_e32 v56, v56
	v_sub_f32_e32 v57, v57, v233
	v_add_f32_e32 v234, v234, v56
	v_exp_f32_e32 v57, v57
	v_sub_f32_e32 v58, v58, v233
	v_add_f32_e32 v234, v234, v57
	v_exp_f32_e32 v58, v58
	v_sub_f32_e32 v59, v59, v233
	v_add_f32_e32 v234, v234, v58
	v_exp_f32_e32 v59, v59
	v_sub_f32_e32 v60, v60, v233
	v_add_f32_e32 v234, v234, v59
	v_exp_f32_e32 v60, v60
	v_sub_f32_e32 v61, v61, v233
	v_add_f32_e32 v234, v234, v60
	v_exp_f32_e32 v61, v61
	v_sub_f32_e32 v62, v62, v233
	v_add_f32_e32 v234, v234, v61
	v_exp_f32_e32 v62, v62
	v_sub_f32_e32 v63, v63, v233
	v_add_f32_e32 v234, v234, v62
	v_exp_f32_e32 v63, v63
	v_sub_f32_e32 v64, v64, v233
	v_add_f32_e32 v234, v234, v63
	v_exp_f32_e32 v64, v64
	v_sub_f32_e32 v65, v65, v233
	v_add_f32_e32 v234, v234, v64
	v_exp_f32_e32 v65, v65
	v_sub_f32_e32 v66, v66, v233
	v_add_f32_e32 v234, v234, v65
	v_exp_f32_e32 v66, v66
	v_sub_f32_e32 v67, v67, v233
	v_add_f32_e32 v234, v234, v66
	v_exp_f32_e32 v67, v67
	v_sub_f32_e32 v68, v68, v233
	v_add_f32_e32 v234, v234, v67
	v_exp_f32_e32 v68, v68
	v_sub_f32_e32 v69, v69, v233
	v_add_f32_e32 v234, v234, v68
	v_exp_f32_e32 v69, v69
	v_sub_f32_e32 v70, v70, v233
	v_add_f32_e32 v234, v234, v69
	v_exp_f32_e32 v70, v70
	v_sub_f32_e32 v71, v71, v233
	v_add_f32_e32 v234, v234, v70
	v_exp_f32_e32 v71, v71
	s_nop 0
	v_add_f32_e32 v234, v234, v71
	ds_bpermute_b32 v235, v223, v234
	v_cvt_pk_bf16_f32 v8, v8, v9
	v_cvt_pk_bf16_f32 v9, v10, v11
	v_cvt_pk_bf16_f32 v10, v12, v13
	v_cvt_pk_bf16_f32 v11, v14, v15
	v_cvt_pk_bf16_f32 v16, v16, v17
	v_cvt_pk_bf16_f32 v17, v18, v19
	v_cvt_pk_bf16_f32 v18, v20, v21
	v_cvt_pk_bf16_f32 v19, v22, v23
	v_cvt_pk_bf16_f32 v24, v24, v25
	v_cvt_pk_bf16_f32 v25, v26, v27
	v_cvt_pk_bf16_f32 v26, v28, v29
	v_cvt_pk_bf16_f32 v27, v30, v31
	v_cvt_pk_bf16_f32 v32, v32, v33
	v_cvt_pk_bf16_f32 v33, v34, v35
	v_cvt_pk_bf16_f32 v34, v36, v37
	v_cvt_pk_bf16_f32 v35, v38, v39
	v_cvt_pk_bf16_f32 v40, v40, v41
	v_cvt_pk_bf16_f32 v41, v42, v43
	v_cvt_pk_bf16_f32 v42, v44, v45
	v_cvt_pk_bf16_f32 v43, v46, v47
	v_cvt_pk_bf16_f32 v48, v48, v49
	v_cvt_pk_bf16_f32 v49, v50, v51
	v_cvt_pk_bf16_f32 v50, v52, v53
	v_cvt_pk_bf16_f32 v51, v54, v55
	v_cvt_pk_bf16_f32 v56, v56, v57
	v_cvt_pk_bf16_f32 v57, v58, v59
	v_cvt_pk_bf16_f32 v58, v60, v61
	v_cvt_pk_bf16_f32 v59, v62, v63
	v_cvt_pk_bf16_f32 v64, v64, v65
	v_cvt_pk_bf16_f32 v65, v66, v67
	v_cvt_pk_bf16_f32 v66, v68, v69
	v_cvt_pk_bf16_f32 v67, v70, v71
	s_waitcnt lgkmcnt(0)
	v_add_f32_e32 v234, v234, v235
	ds_bpermute_b32 v235, v232, v234
	s_waitcnt lgkmcnt(0)
	v_add_f32_e32 v234, v234, v235
	s_barrier
	v_mov_b32_e32 v138, v136
	ds_read_b128 v[12:15], v138 offset:16
	ds_read_b128 v[20:23], v138 offset:16400
	ds_read_b128 v[28:31], v138 offset:32784
	ds_read_b128 v[36:39], v138 offset:49168
	v_xor_b32_e32 v138, 128, v136
	ds_read_b128 v[44:47], v138 offset:16
	ds_read_b128 v[52:55], v138 offset:16400
	ds_read_b128 v[60:63], v138 offset:32784
	ds_read_b128 v[68:71], v138 offset:49168
	v_xor_b32_e32 v138, 256, v136
	ds_read_b128 v[194:197], v138 offset:16
	ds_read_b128 v[198:201], v138 offset:16400
	ds_read_b128 v[202:205], v138 offset:32784
	ds_read_b128 v[206:209], v138 offset:49168
	s_waitcnt lgkmcnt(8)
	v_mfma_f32_16x16x32_bf16 v[178:181], v[12:15], v[8:11], v[178:181]
	v_mfma_f32_16x16x32_bf16 v[182:185], v[20:23], v[8:11], v[182:185]
	v_mfma_f32_16x16x32_bf16 v[186:189], v[28:31], v[8:11], v[186:189]
	v_mfma_f32_16x16x32_bf16 v[190:193], v[36:39], v[8:11], v[190:193]
	v_xor_b32_e32 v138, 384, v136
	ds_read_b128 v[12:15], v138 offset:16
	ds_read_b128 v[20:23], v138 offset:16400
	ds_read_b128 v[28:31], v138 offset:32784
	ds_read_b128 v[36:39], v138 offset:49168
	s_waitcnt lgkmcnt(8)
	v_mfma_f32_16x16x32_bf16 v[178:181], v[44:47], v[16:19], v[178:181]
	v_mfma_f32_16x16x32_bf16 v[182:185], v[52:55], v[16:19], v[182:185]
	v_mfma_f32_16x16x32_bf16 v[186:189], v[60:63], v[16:19], v[186:189]
	v_mfma_f32_16x16x32_bf16 v[190:193], v[68:71], v[16:19], v[190:193]
	v_xor_b32_e32 v138, 512, v136
	ds_read_b128 v[44:47], v138 offset:16
	ds_read_b128 v[52:55], v138 offset:16400
	ds_read_b128 v[60:63], v138 offset:32784
	ds_read_b128 v[68:71], v138 offset:49168
	s_waitcnt lgkmcnt(8)
	v_mfma_f32_16x16x32_bf16 v[178:181], v[194:197], v[24:27], v[178:181]
	v_mfma_f32_16x16x32_bf16 v[182:185], v[198:201], v[24:27], v[182:185]
	v_mfma_f32_16x16x32_bf16 v[186:189], v[202:205], v[24:27], v[186:189]
	v_mfma_f32_16x16x32_bf16 v[190:193], v[206:209], v[24:27], v[190:193]
	v_xor_b32_e32 v138, 640, v136
	ds_read_b128 v[194:197], v138 offset:16
	ds_read_b128 v[198:201], v138 offset:16400
	ds_read_b128 v[202:205], v138 offset:32784
	ds_read_b128 v[206:209], v138 offset:49168
	s_waitcnt lgkmcnt(8)
	v_mfma_f32_16x16x32_bf16 v[178:181], v[12:15], v[32:35], v[178:181]
	v_mfma_f32_16x16x32_bf16 v[182:185], v[20:23], v[32:35], v[182:185]
	v_mfma_f32_16x16x32_bf16 v[186:189], v[28:31], v[32:35], v[186:189]
	v_mfma_f32_16x16x32_bf16 v[190:193], v[36:39], v[32:35], v[190:193]
	v_xor_b32_e32 v138, 768, v136
	ds_read_b128 v[12:15], v138 offset:16
	ds_read_b128 v[20:23], v138 offset:16400
	ds_read_b128 v[28:31], v138 offset:32784
	ds_read_b128 v[36:39], v138 offset:49168
	s_waitcnt lgkmcnt(8)
	v_mfma_f32_16x16x32_bf16 v[178:181], v[44:47], v[40:43], v[178:181]
	v_mfma_f32_16x16x32_bf16 v[182:185], v[52:55], v[40:43], v[182:185]
	v_mfma_f32_16x16x32_bf16 v[186:189], v[60:63], v[40:43], v[186:189]
	v_mfma_f32_16x16x32_bf16 v[190:193], v[68:71], v[40:43], v[190:193]
	v_xor_b32_e32 v138, 896, v136
	ds_read_b128 v[44:47], v138 offset:16
	ds_read_b128 v[52:55], v138 offset:16400
	ds_read_b128 v[60:63], v138 offset:32784
	ds_read_b128 v[68:71], v138 offset:49168
	s_waitcnt lgkmcnt(8)
	v_mfma_f32_16x16x32_bf16 v[178:181], v[194:197], v[48:51], v[178:181]
	v_mfma_f32_16x16x32_bf16 v[182:185], v[198:201], v[48:51], v[182:185]
	v_mfma_f32_16x16x32_bf16 v[186:189], v[202:205], v[48:51], v[186:189]
	v_mfma_f32_16x16x32_bf16 v[190:193], v[206:209], v[48:51], v[190:193]
	s_waitcnt lgkmcnt(4)
	v_mfma_f32_16x16x32_bf16 v[178:181], v[12:15], v[56:59], v[178:181]
	v_mfma_f32_16x16x32_bf16 v[182:185], v[20:23], v[56:59], v[182:185]
	v_mfma_f32_16x16x32_bf16 v[186:189], v[28:31], v[56:59], v[186:189]
	v_mfma_f32_16x16x32_bf16 v[190:193], v[36:39], v[56:59], v[190:193]
	s_waitcnt lgkmcnt(0)
	v_mfma_f32_16x16x32_bf16 v[178:181], v[44:47], v[64:67], v[178:181]
	v_mfma_f32_16x16x32_bf16 v[182:185], v[52:55], v[64:67], v[182:185]
	v_mfma_f32_16x16x32_bf16 v[186:189], v[60:63], v[64:67], v[186:189]
	v_mfma_f32_16x16x32_bf16 v[190:193], v[68:71], v[64:67], v[190:193]
	v_div_scale_f32 v235, s[36:37], v234, v234, 1.0
	v_rcp_f32_e32 v236, v235
	s_nop 0
	v_fma_f32 v237, -v235, v236, 1.0
	v_fmac_f32_e32 v236, v237, v236
	v_div_scale_f32 v237, vcc, 1.0, v234, 1.0
	v_mul_f32_e32 v240, v237, v236
	v_fma_f32 v241, -v235, v240, v237
	v_fmac_f32_e32 v240, v241, v236
	v_fma_f32 v235, -v235, v240, v237
	v_div_fmas_f32 v235, v235, v236, v240
	v_div_fixup_f32 v233, v235, v234, 1.0
	s_nop 3
	v_mul_f32_e32 v178, v178, v233
	v_mul_f32_e32 v179, v179, v233
	v_mul_f32_e32 v180, v180, v233
	v_mul_f32_e32 v181, v181, v233
	v_cvt_pk_bf16_f32 v178, v178, v179
	v_cvt_pk_bf16_f32 v179, v180, v181
	global_store_dwordx2 v222, v[178:179], s[32:33]
	v_mul_f32_e32 v182, v182, v233
	v_mul_f32_e32 v183, v183, v233
	v_mul_f32_e32 v184, v184, v233
	v_mul_f32_e32 v185, v185, v233
	v_cvt_pk_bf16_f32 v182, v182, v183
	v_cvt_pk_bf16_f32 v183, v184, v185
	global_store_dwordx2 v222, v[182:183], s[32:33] offset:32
	v_mul_f32_e32 v186, v186, v233
	v_mul_f32_e32 v187, v187, v233
	v_mul_f32_e32 v188, v188, v233
	v_mul_f32_e32 v189, v189, v233
	v_cvt_pk_bf16_f32 v186, v186, v187
	v_cvt_pk_bf16_f32 v187, v188, v189
	global_store_dwordx2 v222, v[186:187], s[32:33] offset:64
	v_mul_f32_e32 v190, v190, v233
	v_mul_f32_e32 v191, v191, v233
	v_mul_f32_e32 v192, v192, v233
	v_mul_f32_e32 v193, v193, v233
	v_cvt_pk_bf16_f32 v190, v190, v191
	v_cvt_pk_bf16_f32 v191, v192, v193
	global_store_dwordx2 v222, v[190:191], s[32:33] offset:96
	s_add_u32 s14, s14, 1
	s_cmp_lt_u32 s14, 4
	s_cbranch_scc1 .Lna_tile
	v_readlane_b32 s0, v245, 0
	v_readlane_b32 s1, v245, 1
	v_readlane_b32 s2, v245, 2
	v_readlane_b32 s3, v245, 3
	v_readlane_b32 s4, v245, 4
	v_readlane_b32 s5, v245, 5
	v_readlane_b32 s6, v245, 6
	v_readlane_b32 s7, v245, 7
	v_readlane_b32 s8, v245, 8
	v_readlane_b32 s9, v245, 9
	v_readlane_b32 s10, v245, 10
	v_readlane_b32 s11, v245, 11
	v_readlane_b32 s12, v245, 12
	v_readlane_b32 s13, v245, 13
	v_readlane_b32 s14, v245, 14
	v_readlane_b32 s15, v245, 15
	v_readlane_b32 s16, v245, 16
	v_readlane_b32 s17, v245, 17
	v_readlane_b32 s18, v245, 18
	v_readlane_b32 s19, v245, 19
	v_readlane_b32 s20, v245, 20
	v_readlane_b32 s21, v245, 21
	v_readlane_b32 s22, v245, 22
	v_readlane_b32 s23, v245, 23
	v_readlane_b32 s24, v245, 24
	v_readlane_b32 s25, v245, 25
	v_readlane_b32 s26, v245, 26
	v_readlane_b32 s27, v245, 27
	v_readlane_b32 s28, v245, 28
	v_readlane_b32 s29, v245, 29
	v_readlane_b32 s30, v245, 30
	v_readlane_b32 s31, v245, 31
	v_readlane_b32 s32, v245, 32
	v_readlane_b32 s33, v245, 33
	v_readlane_b32 s34, v245, 34
	v_readlane_b32 s35, v245, 35
	v_readlane_b32 s36, v245, 36
	v_readlane_b32 s37, v245, 37
	v_readlane_b32 s38, v245, 38
	v_readlane_b32 s39, v245, 39
	v_readlane_b32 s40, v245, 40
	v_readlane_b32 s41, v245, 41
	v_readlane_b32 s42, v245, 42
	v_readlane_b32 s43, v245, 43
	v_readlane_b32 s44, v245, 44
	v_readlane_b32 s45, v245, 45
	v_readlane_b32 s46, v245, 46
	v_readlane_b32 s47, v245, 47
	v_readlane_b32 s48, v245, 48
	v_readlane_b32 s49, v245, 49
	v_readlane_b32 s50, v245, 50
	v_readlane_b32 s51, v245, 51
	v_readlane_b32 s52, v245, 52
	v_readlane_b32 s53, v245, 53
	v_readlane_b32 s54, v245, 54
	v_readlane_b32 s55, v245, 55
	v_readlane_b32 s56, v245, 56
	v_readlane_b32 s57, v245, 57
	v_readlane_b32 s58, v245, 58
	v_readlane_b32 s59, v245, 59
	v_readlane_b32 s60, v245, 60
	v_readlane_b32 s61, v245, 61
	v_readlane_b32 s62, v245, 62
	v_readlane_b32 s63, v245, 63
	v_readlane_b32 s64, v244, 0
	v_readlane_b32 s65, v244, 1
	v_readlane_b32 s66, v244, 2
	v_readlane_b32 s67, v244, 3
	v_readlane_b32 s68, v244, 4
	v_readlane_b32 s69, v244, 5
	v_readlane_b32 s70, v244, 6
	v_readlane_b32 s71, v244, 7
	v_readlane_b32 s72, v244, 8
	v_readlane_b32 s73, v244, 9
	v_readlane_b32 s74, v244, 10
	v_readlane_b32 s75, v244, 11
	v_readlane_b32 s76, v244, 12
	v_readlane_b32 s77, v244, 13
	v_readlane_b32 s78, v244, 14
	v_readlane_b32 s79, v244, 15
